# xattn key-step loop: S-stage vmcnt ladder removed (Q loads waited once before the loop), K/V prefetch waited after PV MFMAs instead of mid-step
# speedup vs baseline: 1.0057x; 1.0057x over previous
; DI f32x16 zero16() { f32x16 z; for (int i = 0; i < 16; ++i) z[i] = 0.f; return z; }
; DI void phase_xattn(const Params& p, char* lds) {
;     ...
;   for (int item = blockIdx.x; item < 1024; item += gridDim.x) {
;     const int b = item >> 7, h = (item >> 5) & 3, qblk = item & 31;
;     const size_t q0 = (size_t)b * SEQ + qblk * 256 + wave * 32;
;     bf16x8 Qf[16];
; #pragma unroll
;     for (int kk = 0; kk < 16; ++kk) Qf[kk] = ldfrag(XQ + (q0 + l31) * 1024 + h * 256 + kk * 16 + 8 * hh);
;     const u16* kg = KX + ((size_t)b * 256) * 1024 + h * 256;
;     const u16* vg = VTX + ((size_t)((b * 4 + h) * 256)) * 256;
;     {
;       const uint4 k0 = *(const uint4*)(kg + (size_t)kr0 * 1024 + kc), k1 = *(const uint4*)(kg + (size_t)(kr0 + 16) * 1024 + kc);
;       const uint4 v0 = *(const uint4*)(vg + (size_t)vr * 256 + vc);
;       *(uint4*)(Kl + kr0 * 264 + kc) = k0; *(uint4*)(Kl + (kr0 + 16) * 264 + kc) = k1; *(uint4*)(Vl + vr * 40 + vc) = v0;
;     }
;     __syncthreads();
;     f32x16 O[4]; for (int i = 0; i < 4; ++i) O[i] = zero16();
;     float mrun = -INFINITY, lrun = 0.f;
.LBB0_903:
	s_lshl_b32 s6, s13, 8
	s_and_b32 s6, s6, 0x1f00
	s_ashr_i32 s8, s13, 7
	v_lshl_add_u64 v[0:1], v[162:163], 0, s[6:7]
	s_lshl_b32 s6, s13, 3
	s_ashr_i32 s9, s8, 31
	s_and_b32 s16, s6, 0x300
	s_lshl_b64 s[10:11], s[8:9], 24
	s_lshl_b32 s6, s16, 1
	s_lshl_b64 s[14:15], s[8:9], 19
	s_add_u32 s9, s58, s14
	s_addc_u32 s14, s59, s15
	s_add_u32 s18, s9, s6
	s_addc_u32 s19, s14, 0
	s_lshl_b32 s8, s8, 10
	s_or_b32 s8, s16, s8
	s_ashr_i32 s9, s8, 31
	s_lshl_b64 s[8:9], s[8:9], 9
	v_lshlrev_b64 v[0:1], 11, v[0:1]
	s_add_u32 s8, s82, s8
	v_lshl_add_u64 v[2:3], s[18:19], 0, v[166:167]
	v_lshl_add_u64 v[28:29], s[10:11], 0, v[0:1]
	s_addc_u32 s9, s83, s9
	v_lshl_add_u64 v[2:3], v[2:3], 0, v[174:175]
	v_lshl_add_u64 v[4:5], s[18:19], 0, v[168:169]
	v_lshl_add_u64 v[0:1], s[0:1], 0, v[28:29]
	v_lshl_add_u64 v[4:5], v[4:5], 0, v[174:175]
	global_load_dwordx4 v[16:19], v[2:3], off
	global_load_dwordx4 v[20:23], v[4:5], off
	v_lshl_add_u64 v[2:3], s[8:9], 0, v[170:171]
	v_lshl_add_u64 v[0:1], v[0:1], 0, s[6:7]
	v_lshl_add_u64 v[2:3], v[2:3], 0, v[164:165]
	v_lshl_add_u64 v[0:1], v[0:1], 0, v[172:173]
	global_load_dwordx4 v[24:27], v[2:3], off
	global_load_dwordx4 v[92:95], v[0:1], off
	global_load_dwordx4 v[96:99], v[0:1], off offset:32
	global_load_dwordx4 v[100:103], v[0:1], off offset:64
	global_load_dwordx4 v[104:107], v[0:1], off offset:96
	global_load_dwordx4 v[108:111], v[0:1], off offset:128
	global_load_dwordx4 v[112:115], v[0:1], off offset:160
	global_load_dwordx4 v[116:119], v[0:1], off offset:192
	global_load_dwordx4 v[120:123], v[0:1], off offset:224
	global_load_dwordx4 v[124:127], v[0:1], off offset:256
	global_load_dwordx4 v[128:131], v[0:1], off offset:288
	global_load_dwordx4 v[132:135], v[0:1], off offset:320
	global_load_dwordx4 v[136:139], v[0:1], off offset:352
	global_load_dwordx4 v[140:143], v[0:1], off offset:384
	global_load_dwordx4 v[144:147], v[0:1], off offset:416
	global_load_dwordx4 v[148:151], v[0:1], off offset:448
	global_load_dwordx4 v[152:155], v[0:1], off offset:480
	s_add_u32 s10, s56, s6
	s_addc_u32 s11, s57, 0
	v_lshl_add_u64 v[28:29], s[10:11], 0, v[28:29]
	v_mov_b32_e32 v186, 0xff800000
	s_mov_b32 s14, 32
	s_mov_b32 s15, s7
	v_mov_b32_e32 v185, v165
	s_mov_b32 s16, s7
	v_mov_b32_e32 v0, v165
	v_mov_b32_e32 v1, v165
	v_mov_b32_e32 v2, v165
	v_mov_b32_e32 v3, v165
	v_mov_b32_e32 v4, v165
	v_mov_b32_e32 v5, v165
	v_mov_b32_e32 v6, v165
	v_mov_b32_e32 v7, v165
	v_mov_b32_e32 v8, v165
	v_mov_b32_e32 v9, v165
	v_mov_b32_e32 v10, v165
	v_mov_b32_e32 v11, v165
	v_mov_b32_e32 v12, v165
	v_mov_b32_e32 v13, v165
	v_mov_b32_e32 v14, v165
	v_mov_b32_e32 v15, v165
	v_mov_b32_e32 v48, v165
	v_mov_b32_e32 v49, v165
	v_mov_b32_e32 v50, v165
	v_mov_b32_e32 v51, v165
	v_mov_b32_e32 v52, v165
	v_mov_b32_e32 v53, v165
	v_mov_b32_e32 v54, v165
	v_mov_b32_e32 v55, v165
	v_mov_b32_e32 v56, v165
	v_mov_b32_e32 v57, v165
	v_mov_b32_e32 v58, v165
	v_mov_b32_e32 v59, v165
	v_mov_b32_e32 v60, v165
	v_lshl_add_u64 v[178:179], s[18:19], 0, v[174:175]
	v_lshl_add_u64 v[180:181], v[28:29], 0, v[176:177]
	v_mov_b32_e32 v61, v165
	v_mov_b32_e32 v62, v165
	v_mov_b32_e32 v63, v165
	v_mov_b32_e32 v32, v165
	v_mov_b32_e32 v33, v165
	v_mov_b32_e32 v34, v165
	v_mov_b32_e32 v35, v165
	v_mov_b32_e32 v36, v165
	v_mov_b32_e32 v37, v165
	v_mov_b32_e32 v38, v165
	v_mov_b32_e32 v39, v165
	v_mov_b32_e32 v40, v165
	v_mov_b32_e32 v41, v165
	v_mov_b32_e32 v42, v165
	v_mov_b32_e32 v43, v165
	v_mov_b32_e32 v44, v165
	v_mov_b32_e32 v45, v165
	v_mov_b32_e32 v46, v165
	v_mov_b32_e32 v47, v165
	v_mov_b32_e32 v28, v165
	v_mov_b32_e32 v29, v165
	s_waitcnt vmcnt(18)
	ds_write_b128 v159, v[16:19]
	s_waitcnt vmcnt(17)
	ds_write_b128 v159, v[20:23] offset:8448
	s_waitcnt vmcnt(16)
	ds_write_b128 v161, v[24:27] offset:33792
	v_mov_b32_e32 v16, v165
	v_mov_b32_e32 v17, v165
	v_mov_b32_e32 v18, v165
	v_mov_b32_e32 v19, v165
	v_mov_b32_e32 v20, v165
	v_mov_b32_e32 v21, v165
	v_mov_b32_e32 v22, v165
	v_mov_b32_e32 v23, v165
	v_mov_b32_e32 v24, v165
	v_mov_b32_e32 v25, v165
	v_mov_b32_e32 v26, v165
	v_mov_b32_e32 v27, v165
	v_mov_b32_e32 v30, v165
	v_mov_b32_e32 v31, v165
	s_waitcnt vmcnt(0) lgkmcnt(0)
	s_barrier
	s_cmpk_lg_i32 s15, 0xf0
	s_cselect_b64 s[10:11], -1, 0
	s_cmpk_eq_i32 s15, 0xf0
	s_cbranch_scc1 .LBB0_905

; #define MFMA(a, b, c) __builtin_amdgcn_mfma_f32_32x32x16_bf16((a), (b), (c), 0, 0, 0)
; DI unsigned pack2(float a, float b) { const f32x2 v = {a, b}; return __builtin_bit_cast(unsigned, __builtin_convertvector(v, bf16v2)); }
; DI f32x16 zero16() { f32x16 z; for (int i = 0; i < 16; ++i) z[i] = 0.f; return z; }
; DI void phase_xattn(const Params& p, char* lds) {
;     ...
;       const u16* kl = Kl + cur * 32 * 264 + pi * 264 + 8 * hh;
;       const u16* vl = Vl + cur * 128 * 40 + l31 * 40 + 8 * hh;
;       f32x16 S = zero16();
; #pragma unroll
;       for (int kk = 0; kk < 16; ++kk) S = MFMA(ldfrag(kl + kk * 16), Qf[kk], S);
;       float mx = -INFINITY;
; #pragma unroll
;       for (int r = 0; r < 16; ++r) { S[r] *= 0.09016844005556021f; mx = fmaxf(mx, S[r]); }
;       mx = fmaxf(mx, __shfl_xor(mx, 32));
;       const float mnew = fmaxf(mrun, mx), alpha = __builtin_amdgcn_exp2f(mrun - mnew);
;       mrun = mnew;
;       float ps = 0.f;
; #pragma unroll
;       for (int r = 0; r < 16; ++r) { const float e = __builtin_amdgcn_exp2f(S[r] - mnew); S[r] = e; ps += e; }
;       lrun = lrun * alpha + ps;
;       bf16x8 Pf[2];
; #pragma unroll
;       for (int ks = 0; ks < 2; ++ks) {
;         union { bf16x8 v; unsigned u[4]; } cv;
;         for (int j2 = 0; j2 < 4; ++j2) cv.u[j2] = pack2(S[8 * ks + 2 * j2], S[8 * ks + 2 * j2 + 1]);
;         Pf[ks] = cv.v;
;       }
; #pragma unroll
;       for (int dt = 0; dt < 4; ++dt) {
; #pragma unroll
;         for (int r = 0; r < 16; ++r) O[dt][r] *= alpha;
; #pragma unroll
;         for (int ks = 0; ks < 2; ++ks) O[dt] = MFMA(ldfrag(vl + dt * 32 * 40 + 16 * ks), Pf[ks], O[dt]);
.LBB0_905:
	s_and_b32 s17, s16, 1
	s_mul_i32 s6, s17, 0x4200
	v_add_u32_e32 v187, s6, v182
	ds_read_b128 v[64:67], v187
	ds_read_b128 v[188:191], v187 offset:32
	s_mul_i32 s6, s17, 0x2800
	v_add_u32_e32 v200, s6, v183
	s_and_b32 s6, s16, 7
	s_waitcnt lgkmcnt(1)
	v_mfma_f32_32x32x16_bf16 v[64:79], v[64:67], v[92:95], 0
	s_cmp_lg_u32 s6, 7
	s_waitcnt lgkmcnt(0)
	v_mfma_f32_32x32x16_bf16 v[64:79], v[188:191], v[96:99], v[64:79]
	ds_read_b128 v[188:191], v187 offset:64
	ds_read_b128 v[192:195], v187 offset:96
	s_waitcnt lgkmcnt(1)
	v_mfma_f32_32x32x16_bf16 v[64:79], v[188:191], v[100:103], v[64:79]
	s_waitcnt lgkmcnt(0)
	v_mfma_f32_32x32x16_bf16 v[64:79], v[192:195], v[104:107], v[64:79]
	ds_read_b128 v[188:191], v187 offset:128
	ds_read_b128 v[192:195], v187 offset:160
	s_waitcnt lgkmcnt(1)
	v_mfma_f32_32x32x16_bf16 v[64:79], v[188:191], v[108:111], v[64:79]
	s_waitcnt lgkmcnt(0)
	v_mfma_f32_32x32x16_bf16 v[64:79], v[192:195], v[112:115], v[64:79]
	ds_read_b128 v[188:191], v187 offset:192
	ds_read_b128 v[192:195], v187 offset:224
	s_waitcnt lgkmcnt(1)
	v_mfma_f32_32x32x16_bf16 v[64:79], v[188:191], v[116:119], v[64:79]
	s_waitcnt lgkmcnt(0)
	v_mfma_f32_32x32x16_bf16 v[64:79], v[192:195], v[120:123], v[64:79]
	ds_read_b128 v[188:191], v187 offset:256
	ds_read_b128 v[192:195], v187 offset:288
	s_waitcnt lgkmcnt(1)
	v_mfma_f32_32x32x16_bf16 v[64:79], v[188:191], v[124:127], v[64:79]
	s_waitcnt lgkmcnt(0)
	v_mfma_f32_32x32x16_bf16 v[64:79], v[192:195], v[128:131], v[64:79]
	ds_read_b128 v[188:191], v187 offset:320
	ds_read_b128 v[192:195], v187 offset:352
	s_waitcnt lgkmcnt(1)
	v_mfma_f32_32x32x16_bf16 v[64:79], v[188:191], v[132:135], v[64:79]
	s_waitcnt lgkmcnt(0)
	v_mfma_f32_32x32x16_bf16 v[64:79], v[192:195], v[136:139], v[64:79]
	ds_read_b128 v[188:191], v187 offset:384
	ds_read_b128 v[192:195], v187 offset:416
	s_waitcnt lgkmcnt(1)
	v_mfma_f32_32x32x16_bf16 v[64:79], v[188:191], v[140:143], v[64:79]
	s_waitcnt lgkmcnt(0)
	v_mfma_f32_32x32x16_bf16 v[64:79], v[192:195], v[144:147], v[64:79]
	ds_read_b128 v[188:191], v187 offset:448
	ds_read_b128 v[192:195], v187 offset:480
	s_waitcnt lgkmcnt(1)
	v_mfma_f32_32x32x16_bf16 v[64:79], v[188:191], v[148:151], v[64:79]
	ds_read_b128 v[188:191], v200 offset:33792
	ds_read_b128 v[196:199], v200 offset:33824
	s_waitcnt lgkmcnt(2)
	v_mfma_f32_32x32x16_bf16 v[64:79], v[192:195], v[152:155], v[64:79]
	s_nop 11
	v_mul_f32_e32 v187, 0x3db8aa3b, v64
	v_mul_f32_e32 v192, 0x3db8aa3b, v65
	v_mul_f32_e32 v193, 0x3db8aa3b, v66
	v_mul_f32_e32 v194, 0x3db8aa3b, v67
	v_max3_f32 v187, v187, s12, v192
	v_mul_f32_e32 v195, 0x3db8aa3b, v68
	v_mul_f32_e32 v201, 0x3db8aa3b, v69
	v_max3_f32 v187, v187, v193, v194
	v_mul_f32_e32 v202, 0x3db8aa3b, v70
	v_mul_f32_e32 v204, 0x3db8aa3b, v71
	v_max3_f32 v187, v187, v195, v201
	v_mul_f32_e32 v205, 0x3db8aa3b, v72
	v_mul_f32_e32 v206, 0x3db8aa3b, v73
	v_max3_f32 v187, v187, v202, v204
	v_mul_f32_e32 v207, 0x3db8aa3b, v74
	v_mul_f32_e32 v208, 0x3db8aa3b, v75
	v_max3_f32 v187, v187, v205, v206
	v_mul_f32_e32 v209, 0x3db8aa3b, v76
	v_mul_f32_e32 v210, 0x3db8aa3b, v77
	v_max3_f32 v187, v187, v207, v208
	v_mul_f32_e32 v211, 0x3db8aa3b, v78
	v_mul_f32_e32 v212, 0x3db8aa3b, v79
	v_max3_f32 v187, v187, v209, v210
	v_max3_f32 v187, v187, v211, v212
	ds_bpermute_b32 v201, v184, v187
	ds_read_b128 v[192:195], v200 offset:36352
	ds_read_b128 v[204:207], v200 offset:36384
	ds_read_b128 v[208:211], v200 offset:38912
	ds_read_b128 v[212:215], v200 offset:38944
	s_waitcnt lgkmcnt(4)
	v_max3_f32 v187, v186, v187, v201
	v_fma_f32 v64, v64, s2, -v187
	v_fma_f32 v65, v65, s2, -v187
	v_exp_f32_e32 v201, v64
	v_fma_f32 v66, v66, s2, -v187
	v_exp_f32_e32 v202, v65
	v_fma_f32 v67, v67, s2, -v187
	v_exp_f32_e32 v216, v66
	v_fma_f32 v68, v68, s2, -v187
	v_fma_f32 v76, v76, s2, -v187
	v_exp_f32_e32 v217, v67
	v_fma_f32 v69, v69, s2, -v187
	v_exp_f32_e32 v218, v68
	v_exp_f32_e32 v227, v76
	v_add_f32_e32 v76, 0, v201
	v_fma_f32 v70, v70, s2, -v187
	v_fma_f32 v72, v72, s2, -v187
	v_fma_f32 v73, v73, s2, -v187
	v_fma_f32 v74, v74, s2, -v187
	v_fma_f32 v75, v75, s2, -v187
	v_exp_f32_e32 v219, v69
	v_add_f32_e32 v76, v202, v76
	v_fma_f32 v71, v71, s2, -v187
	v_exp_f32_e32 v220, v70
	v_exp_f32_e32 v223, v72
	v_exp_f32_e32 v224, v73
	v_exp_f32_e32 v225, v74
	v_exp_f32_e32 v226, v75
	ds_read_b128 v[72:75], v200 offset:41472
	v_add_f32_e32 v76, v216, v76
	v_exp_f32_e32 v221, v71
	v_add_f32_e32 v76, v217, v76
	v_sub_f32_e32 v186, v186, v187
	v_add_f32_e32 v76, v218, v76
	v_exp_f32_e32 v186, v186
	v_add_f32_e32 v76, v219, v76
	v_add_f32_e32 v76, v220, v76
	v_add_f32_e32 v76, v221, v76
	v_add_f32_e32 v76, v223, v76
	v_fma_f32 v77, v77, s2, -v187
	v_fma_f32 v78, v78, s2, -v187
	v_fma_f32 v79, v79, s2, -v187
	v_cvt_pk_bf16_f32 v64, v201, v202
	v_cvt_pk_bf16_f32 v65, v216, v217
	v_cvt_pk_bf16_f32 v66, v218, v219
	v_cvt_pk_bf16_f32 v67, v220, v221
	v_pk_mul_f32 v[62:63], v[62:63], v[186:187] op_sel_hi:[1,0]
	v_pk_mul_f32 v[60:61], v[60:61], v[186:187] op_sel_hi:[1,0]
	v_pk_mul_f32 v[58:59], v[58:59], v[186:187] op_sel_hi:[1,0]
	v_pk_mul_f32 v[56:57], v[56:57], v[186:187] op_sel_hi:[1,0]
	v_pk_mul_f32 v[54:55], v[54:55], v[186:187] op_sel_hi:[1,0]
	v_pk_mul_f32 v[52:53], v[52:53], v[186:187] op_sel_hi:[1,0]
	v_pk_mul_f32 v[50:51], v[50:51], v[186:187] op_sel_hi:[1,0]
	v_pk_mul_f32 v[48:49], v[48:49], v[186:187] op_sel_hi:[1,0]
	v_add_f32_e32 v76, v224, v76
	v_pk_mul_f32 v[14:15], v[14:15], v[186:187] op_sel_hi:[1,0]
	v_pk_mul_f32 v[12:13], v[12:13], v[186:187] op_sel_hi:[1,0]
	v_mfma_f32_32x32x16_bf16 v[48:63], v[188:191], v[64:67], v[48:63]
	v_mul_f32_e64 v10, v10, v186
	v_mul_f32_e64 v11, v11, v186
	v_mul_f32_e64 v8, v8, v186
	v_mul_f32_e64 v9, v9, v186
	v_mul_f32_e64 v6, v6, v186
	v_mul_f32_e64 v7, v7, v186
	v_pk_mul_f32 v[4:5], v[4:5], v[186:187] op_sel_hi:[1,0]
	v_pk_mul_f32 v[2:3], v[2:3], v[186:187] op_sel_hi:[1,0]
	v_pk_mul_f32 v[0:1], v[0:1], v[186:187] op_sel_hi:[1,0]
	v_pk_mul_f32 v[46:47], v[46:47], v[186:187] op_sel_hi:[1,0]
	v_pk_mul_f32 v[44:45], v[44:45], v[186:187] op_sel_hi:[1,0]
	v_pk_mul_f32 v[42:43], v[42:43], v[186:187] op_sel_hi:[1,0]
	v_pk_mul_f32 v[40:41], v[40:41], v[186:187] op_sel_hi:[1,0]
	v_pk_mul_f32 v[38:39], v[38:39], v[186:187] op_sel_hi:[1,0]
	v_pk_mul_f32 v[36:37], v[36:37], v[186:187] op_sel_hi:[1,0]
	v_pk_mul_f32 v[34:35], v[34:35], v[186:187] op_sel_hi:[1,0]
	v_pk_mul_f32 v[32:33], v[32:33], v[186:187] op_sel_hi:[1,0]
	v_exp_f32_e32 v188, v77
	v_exp_f32_e32 v189, v78
	v_exp_f32_e32 v190, v79
	v_pk_mul_f32 v[30:31], v[30:31], v[186:187] op_sel_hi:[1,0]
	v_add_f32_e32 v191, v225, v76
	v_pk_mul_f32 v[28:29], v[28:29], v[186:187] op_sel_hi:[1,0]
	v_pk_mul_f32 v[26:27], v[26:27], v[186:187] op_sel_hi:[1,0]
	v_pk_mul_f32 v[24:25], v[24:25], v[186:187] op_sel_hi:[1,0]
	v_pk_mul_f32 v[22:23], v[22:23], v[186:187] op_sel_hi:[1,0]
	v_pk_mul_f32 v[20:21], v[20:21], v[186:187] op_sel_hi:[1,0]
	v_pk_mul_f32 v[18:19], v[18:19], v[186:187] op_sel_hi:[1,0]
	v_pk_mul_f32 v[16:17], v[16:17], v[186:187] op_sel_hi:[1,0]
	ds_read_b128 v[76:79], v200 offset:41504
	s_waitcnt lgkmcnt(5)
; #define MFMA(a, b, c) __builtin_amdgcn_mfma_f32_32x32x16_bf16((a), (b), (c), 0, 0, 0)
; DI unsigned pack2(float a, float b) { const f32x2 v = {a, b}; return __builtin_bit_cast(unsigned, __builtin_convertvector(v, bf16v2)); }
; DI f32x16 zero16() { f32x16 z; for (int i = 0; i < 16; ++i) z[i] = 0.f; return z; }
; DI void phase_xattn(const Params& p, char* lds) {
;     ...
; #pragma unroll
;       for (int dt = 0; dt < 4; ++dt) {
; #pragma unroll
;         for (int r = 0; r < 16; ++r) O[dt][r] *= alpha;
; #pragma unroll
;         for (int ks = 0; ks < 2; ++ks) O[dt] = MFMA(ldfrag(vl + dt * 32 * 40 + 16 * ks), Pf[ks], O[dt]);
;       }
;       if (kt == 7) {
;         const float inv = __builtin_amdgcn_rcpf(lrun + __shfl_xor(lrun, 32));
; #pragma unroll
;         for (int dt = 0; dt < 4; ++dt) {
; #pragma unroll
;           for (int g = 0; g < 4; ++g) {
;             uint2 o; o.x = pack2(O[dt][4 * g] * inv, O[dt][4 * g + 1] * inv); o.y = pack2(O[dt][4 * g + 2] * inv, O[dt][4 * g + 3] * inv);
;             *(uint2*)(XO + (q0 + l31) * 1024 + h * 256 + dh * 128 + dt * 32 + 8 * g + 4 * hh) = o;
;           }
;           O[dt] = zero16();
;         }
;         mrun = -INFINITY; lrun = 0.f;
;       }
;       if (st < 15) {
;         const int nx = cur ^ 1;
;         *(uint4*)(Kl + nx * 32 * 264 + kr0 * 264 + kc) = nk0; *(uint4*)(Kl + nx * 32 * 264 + (kr0 + 16) * 264 + kc) = nk1; *(uint4*)(Vl + nx * 128 * 40 + vr * 40 + vc) = nv0;
;       }
;       __syncthreads();
	v_mfma_f32_32x32x16_bf16 v[0:15], v[192:195], v[64:67], v[0:15]
	v_cvt_pk_bf16_f32 v68, v223, v224
	v_cvt_pk_bf16_f32 v69, v225, v226
	v_cvt_pk_bf16_f32 v70, v227, v188
	v_cvt_pk_bf16_f32 v71, v189, v190
	s_waitcnt lgkmcnt(3)
	v_mfma_f32_32x32x16_bf16 v[32:47], v[208:211], v[64:67], v[32:47]
	s_waitcnt lgkmcnt(1)
	v_mfma_f32_32x32x16_bf16 v[16:31], v[72:75], v[64:67], v[16:31]
	v_add_f32_e32 v64, v226, v191
	v_add_f32_e32 v64, v227, v64
	v_add_f32_e32 v64, v188, v64
	v_add_f32_e32 v64, v189, v64
	v_add_f32_e32 v64, v190, v64
	v_fmac_f32_e32 v64, v185, v186
	v_mfma_f32_32x32x16_bf16 v[48:63], v[196:199], v[68:71], v[48:63]
	v_mfma_f32_32x32x16_bf16 v[0:15], v[204:207], v[68:71], v[0:15]
	v_mfma_f32_32x32x16_bf16 v[32:47], v[212:215], v[68:71], v[32:47]
	s_waitcnt lgkmcnt(0)
	v_mfma_f32_32x32x16_bf16 v[16:31], v[76:79], v[68:71], v[16:31]
	s_waitcnt vmcnt(0)
	s_cbranch_scc1 .LBB0_907
	ds_bpermute_b32 v65, v184, v64
	s_and_b32 s6, s15, 0x80
	s_lshl_b32 s6, s6, 1
	v_lshl_add_u64 v[66:67], v[180:181], 0, s[6:7]
	v_mov_b32_e32 v187, 0xff800000
	s_waitcnt lgkmcnt(0)
	v_add_f32_e32 v64, v64, v65
	v_rcp_f32_e32 v64, v64
	s_nop 0
	v_pk_mul_f32 v[0:1], v[0:1], v[64:65] op_sel_hi:[1,0]
	v_pk_mul_f32 v[2:3], v[2:3], v[64:65] op_sel_hi:[1,0]
	v_cvt_pk_bf16_f32 v0, v0, v1
	v_cvt_pk_bf16_f32 v1, v2, v3
	global_store_dwordx2 v[66:67], v[0:1], off offset:64
	v_pk_mul_f32 v[0:1], v[4:5], v[64:65] op_sel_hi:[1,0]
	v_pk_mul_f32 v[2:3], v[6:7], v[64:65] op_sel_hi:[1,0]
	v_cvt_pk_bf16_f32 v0, v0, v1
	v_cvt_pk_bf16_f32 v1, v2, v3
	global_store_dwordx2 v[66:67], v[0:1], off offset:80
	v_pk_mul_f32 v[0:1], v[8:9], v[64:65] op_sel_hi:[1,0]
	v_pk_mul_f32 v[2:3], v[10:11], v[64:65] op_sel_hi:[1,0]
	v_cvt_pk_bf16_f32 v0, v0, v1
	v_cvt_pk_bf16_f32 v1, v2, v3
	global_store_dwordx2 v[66:67], v[0:1], off offset:96
	v_pk_mul_f32 v[0:1], v[12:13], v[64:65] op_sel_hi:[1,0]
	v_pk_mul_f32 v[2:3], v[14:15], v[64:65] op_sel_hi:[1,0]
	v_cvt_pk_bf16_f32 v0, v0, v1
	v_cvt_pk_bf16_f32 v1, v2, v3
	global_store_dwordx2 v[66:67], v[0:1], off offset:112
	v_pk_mul_f32 v[0:1], v[32:33], v[64:65] op_sel_hi:[1,0]
	v_pk_mul_f32 v[2:3], v[34:35], v[64:65] op_sel_hi:[1,0]
	v_cvt_pk_bf16_f32 v0, v0, v1
	v_cvt_pk_bf16_f32 v1, v2, v3
	global_store_dwordx2 v[66:67], v[0:1], off offset:128
	v_pk_mul_f32 v[0:1], v[36:37], v[64:65] op_sel_hi:[1,0]
	v_pk_mul_f32 v[2:3], v[38:39], v[64:65] op_sel_hi:[1,0]
	v_cvt_pk_bf16_f32 v0, v0, v1
	v_cvt_pk_bf16_f32 v1, v2, v3
	global_store_dwordx2 v[66:67], v[0:1], off offset:144
	v_pk_mul_f32 v[0:1], v[40:41], v[64:65] op_sel_hi:[1,0]
	v_pk_mul_f32 v[2:3], v[42:43], v[64:65] op_sel_hi:[1,0]
	v_cvt_pk_bf16_f32 v0, v0, v1
	v_cvt_pk_bf16_f32 v1, v2, v3
	global_store_dwordx2 v[66:67], v[0:1], off offset:160
	v_pk_mul_f32 v[0:1], v[44:45], v[64:65] op_sel_hi:[1,0]
	v_pk_mul_f32 v[2:3], v[46:47], v[64:65] op_sel_hi:[1,0]
	v_cvt_pk_bf16_f32 v0, v0, v1
	v_cvt_pk_bf16_f32 v1, v2, v3
	v_pk_mul_f32 v[48:49], v[48:49], v[64:65] op_sel_hi:[1,0]
	v_pk_mul_f32 v[50:51], v[50:51], v[64:65] op_sel_hi:[1,0]
	global_store_dwordx2 v[66:67], v[0:1], off offset:176
	v_pk_mul_f32 v[0:1], v[16:17], v[64:65] op_sel_hi:[1,0]
	v_pk_mul_f32 v[2:3], v[18:19], v[64:65] op_sel_hi:[1,0]
	v_cvt_pk_bf16_f32 v48, v48, v49
	v_cvt_pk_bf16_f32 v49, v50, v51
	v_cvt_pk_bf16_f32 v0, v0, v1
	v_cvt_pk_bf16_f32 v1, v2, v3
	v_pk_mul_f32 v[52:53], v[52:53], v[64:65] op_sel_hi:[1,0]
	global_store_dwordx2 v[66:67], v[48:49], off
	v_pk_mul_f32 v[48:49], v[54:55], v[64:65] op_sel_hi:[1,0]
	global_store_dwordx2 v[66:67], v[0:1], off offset:192
	v_pk_mul_f32 v[0:1], v[20:21], v[64:65] op_sel_hi:[1,0]
	v_pk_mul_f32 v[2:3], v[22:23], v[64:65] op_sel_hi:[1,0]
	v_cvt_pk_bf16_f32 v50, v52, v53
	v_cvt_pk_bf16_f32 v51, v48, v49
	v_cvt_pk_bf16_f32 v0, v0, v1
	v_cvt_pk_bf16_f32 v1, v2, v3
	global_store_dwordx2 v[66:67], v[50:51], off offset:16
	v_pk_mul_f32 v[48:49], v[56:57], v[64:65] op_sel_hi:[1,0]
	v_pk_mul_f32 v[50:51], v[58:59], v[64:65] op_sel_hi:[1,0]
	global_store_dwordx2 v[66:67], v[0:1], off offset:208
	v_pk_mul_f32 v[0:1], v[24:25], v[64:65] op_sel_hi:[1,0]
	v_pk_mul_f32 v[2:3], v[26:27], v[64:65] op_sel_hi:[1,0]
	v_cvt_pk_bf16_f32 v48, v48, v49
	v_cvt_pk_bf16_f32 v49, v50, v51
	v_cvt_pk_bf16_f32 v0, v0, v1
	v_cvt_pk_bf16_f32 v1, v2, v3
	global_store_dwordx2 v[66:67], v[48:49], off offset:32
	v_pk_mul_f32 v[48:49], v[60:61], v[64:65] op_sel_hi:[1,0]
	v_pk_mul_f32 v[50:51], v[62:63], v[64:65] op_sel_hi:[1,0]
	global_store_dwordx2 v[66:67], v[0:1], off offset:224
	v_pk_mul_f32 v[0:1], v[28:29], v[64:65] op_sel_hi:[1,0]
	v_pk_mul_f32 v[2:3], v[30:31], v[64:65] op_sel_hi:[1,0]
	v_cvt_pk_bf16_f32 v48, v48, v49
	v_cvt_pk_bf16_f32 v49, v50, v51
	v_cvt_pk_bf16_f32 v0, v0, v1
	v_cvt_pk_bf16_f32 v1, v2, v3
	v_mov_b32_e32 v64, 0
	global_store_dwordx2 v[66:67], v[48:49], off offset:48
	global_store_dwordx2 v[66:67], v[0:1], off offset:240
	v_mov_b32_e32 v0, 0
	v_mov_b32_e32 v1, v64
	v_mov_b32_e32 v2, v64
	v_mov_b32_e32 v3, v64
	v_mov_b32_e32 v4, v64
	v_mov_b32_e32 v5, v64
	v_mov_b32_e32 v6, v64
	v_mov_b32_e32 v7, v64
	v_mov_b32_e32 v8, v64
	v_mov_b32_e32 v9, v64
	v_mov_b32_e32 v10, v64
	v_mov_b32_e32 v11, v64
	v_mov_b32_e32 v12, v64
	v_mov_b32_e32 v13, v64
	v_mov_b32_e32 v14, v64
	v_mov_b32_e32 v15, v64
	v_mov_b32_e32 v48, 0
	v_mov_b32_e32 v49, v64
	v_mov_b32_e32 v50, v64
	v_mov_b32_e32 v51, v64
	v_mov_b32_e32 v52, v64
	v_mov_b32_e32 v53, v64
	v_mov_b32_e32 v54, v64
	v_mov_b32_e32 v55, v64
	v_mov_b32_e32 v56, v64
	v_mov_b32_e32 v57, v64
	v_mov_b32_e32 v58, v64
	v_mov_b32_e32 v59, v64
	v_mov_b32_e32 v60, v64
	v_mov_b32_e32 v61, v64
	v_mov_b32_e32 v62, v64
	v_mov_b32_e32 v63, v64
	v_mov_b32_e32 v32, 0
	v_mov_b32_e32 v33, v64
	v_mov_b32_e32 v34, v64
	v_mov_b32_e32 v35, v64
	v_mov_b32_e32 v36, v64
	v_mov_b32_e32 v37, v64
	v_mov_b32_e32 v38, v64
	v_mov_b32_e32 v39, v64
	v_mov_b32_e32 v40, v64
	v_mov_b32_e32 v41, v64
	v_mov_b32_e32 v42, v64
	v_mov_b32_e32 v43, v64
	v_mov_b32_e32 v44, v64
	v_mov_b32_e32 v45, v64
	v_mov_b32_e32 v46, v64
	v_mov_b32_e32 v47, v64
	v_mov_b32_e32 v16, 0
	v_mov_b32_e32 v17, v64
	v_mov_b32_e32 v18, v64
	v_mov_b32_e32 v19, v64
	v_mov_b32_e32 v20, v64
	v_mov_b32_e32 v21, v64
	v_mov_b32_e32 v22, v64
	v_mov_b32_e32 v23, v64
	v_mov_b32_e32 v24, v64
	v_mov_b32_e32 v25, v64
	v_mov_b32_e32 v26, v64
	v_mov_b32_e32 v27, v64
	v_mov_b32_e32 v28, v64
	v_mov_b32_e32 v29, v64
	v_mov_b32_e32 v30, v64
	v_mov_b32_e32 v31, v64
